# xl_minigemm epilogue stores widened: v_permlane32_swap pairs column groups so eight dwordx2 stores per thread become four dwordx4
# speedup vs baseline: 1.0072x; 1.0072x over previous
.LBB0_647:
	v_or_b32_e32 v66, s1, v1
	v_ashrrev_i32_e32 v67, 31, v66
	v_lshlrev_b64 v[68:69], 6, v[66:67]
	v_lshl_add_u64 v[80:81], s[24:25], 0, v[68:69]
	v_or_b32_e32 v116, 32, v66
	v_ashrrev_i32_e32 v117, 31, v116
	v_lshlrev_b64 v[118:119], 6, v[116:117]
	v_lshl_add_u64 v[114:115], s[24:25], 0, v[118:119]
	global_load_dwordx4 v[68:71], v[80:81], off offset:48
	global_load_dwordx4 v[72:75], v[80:81], off offset:32
	global_load_dwordx4 v[76:79], v[80:81], off offset:16
	s_nop 0
	global_load_dwordx4 v[80:83], v[80:81], off
	global_load_dwordx4 v[98:101], v[114:115], off offset:48
	global_load_dwordx4 v[102:105], v[114:115], off offset:32
	global_load_dwordx4 v[106:109], v[114:115], off offset:16
	global_load_dwordx4 v[110:113], v[114:115], off
	s_add_i32 s0, s0, s87
	s_cmpk_gt_i32 s0, 0xff
	s_waitcnt vmcnt(6)
	v_add_f32_e32 v72, v72, v73
	v_add_f32_e32 v74, v74, v75
	s_waitcnt vmcnt(4)
	v_mov_b32_e32 v84, v81
	v_mov_b32_e32 v85, v82
	v_mov_b32_e32 v81, v83
	v_mov_b32_e32 v82, v77
	v_mov_b32_e32 v83, v78
	v_mov_b32_e32 v77, v79
	v_pk_add_f32 v[80:81], v[84:85], v[80:81]
	v_pk_add_f32 v[76:77], v[82:83], v[76:77]
	v_pk_add_f32 v[80:81], v[80:81], v[80:81] op_sel:[0,1] op_sel_hi:[1,0]
	v_pk_add_f32 v[76:77], v[76:77], v[76:77] op_sel:[0,1] op_sel_hi:[1,0]
	v_mov_b32_e32 v81, v68
	v_mov_b32_e32 v77, v69
	v_mov_b32_e32 v73, v70
	v_mov_b32_e32 v75, v71
	v_pk_add_f32 v[68:69], v[80:81], v[76:77]
	v_pk_add_f32 v[70:71], v[72:73], v[74:75]
	s_nop 0
	v_pk_add_f32 v[68:69], v[68:69], v[70:71]
	v_lshlrev_b64 v[70:71], 9, v[66:67]
	v_add_f32_e32 v68, v68, v69
	v_fmamk_f32 v68, v68, 0x3a800000, v220
	v_rsq_f32_e32 v68, v68
	v_lshl_add_u64 v[70:71], v[164:165], 0, v[70:71]
	s_waitcnt vmcnt(0)
	v_add_f32_e32 v102, v102, v103
	v_add_f32_e32 v104, v104, v105
	v_mov_b32_e32 v120, v111
	v_mov_b32_e32 v121, v112
	v_mov_b32_e32 v111, v113
	v_mov_b32_e32 v112, v107
	v_mov_b32_e32 v113, v108
	v_mov_b32_e32 v107, v109
	v_pk_add_f32 v[110:111], v[120:121], v[110:111]
	v_pk_add_f32 v[106:107], v[112:113], v[106:107]
	v_pk_add_f32 v[110:111], v[110:111], v[110:111] op_sel:[0,1] op_sel_hi:[1,0]
	v_pk_add_f32 v[106:107], v[106:107], v[106:107] op_sel:[0,1] op_sel_hi:[1,0]
	v_mov_b32_e32 v111, v98
	v_mov_b32_e32 v107, v99
	v_mov_b32_e32 v103, v100
	v_mov_b32_e32 v105, v101
	v_pk_add_f32 v[98:99], v[110:111], v[106:107]
	v_pk_add_f32 v[100:101], v[102:103], v[104:105]
	s_nop 0
	v_pk_add_f32 v[98:99], v[98:99], v[100:101]
	v_lshlrev_b64 v[100:101], 9, v[116:117]
	v_add_f32_e32 v98, v98, v99
	v_fmamk_f32 v98, v98, 0x3a800000, v220
	v_rsq_f32_e32 v98, v98
	v_lshl_add_u64 v[100:101], v[164:165], 0, v[100:101]
	v_mbcnt_lo_u32_b32 v118, -1, 0
	v_mbcnt_hi_u32_b32 v118, -1, v118
	v_and_b32_e32 v118, 32, v118
	v_lshrrev_b32_e32 v118, 2, v118
	v_add_co_u32_e32 v70, vcc, v70, v118
	s_nop 1
	v_addc_co_u32_e32 v71, vcc, 0, v71, vcc
	v_add_co_u32_e32 v100, vcc, v100, v118
	s_nop 1
	v_addc_co_u32_e32 v101, vcc, 0, v101, vcc
	v_pk_mul_f32 v[18:19], v[18:19], v[68:69] op_sel_hi:[1,0]
	v_pk_mul_f32 v[20:21], v[20:21], v[68:69] op_sel_hi:[1,0]
	v_cvt_pk_bf16_f32 v18, v18, v19
	v_cvt_pk_bf16_f32 v19, v20, v21
	v_pk_mul_f32 v[22:23], v[22:23], v[68:69] op_sel_hi:[1,0]
	v_pk_mul_f32 v[24:25], v[24:25], v[68:69] op_sel_hi:[1,0]
	v_cvt_pk_bf16_f32 v20, v22, v23
	v_cvt_pk_bf16_f32 v21, v24, v25
	s_nop 1
	v_permlane32_swap_b32 v18, v20
	v_permlane32_swap_b32 v19, v21
	global_store_dwordx4 v[70:71], v[18:21], off
	v_pk_mul_f32 v[26:27], v[26:27], v[68:69] op_sel_hi:[1,0]
	v_pk_mul_f32 v[28:29], v[28:29], v[68:69] op_sel_hi:[1,0]
	v_cvt_pk_bf16_f32 v22, v26, v27
	v_cvt_pk_bf16_f32 v23, v28, v29
	v_pk_mul_f32 v[30:31], v[30:31], v[68:69] op_sel_hi:[1,0]
	v_pk_mul_f32 v[32:33], v[32:33], v[68:69] op_sel_hi:[1,0]
	v_cvt_pk_bf16_f32 v24, v30, v31
	v_cvt_pk_bf16_f32 v25, v32, v33
	s_nop 1
	v_permlane32_swap_b32 v22, v24
	v_permlane32_swap_b32 v23, v25
	global_store_dwordx4 v[70:71], v[22:25], off offset:32
	v_pk_mul_f32 v[2:3], v[2:3], v[98:99] op_sel_hi:[1,0]
	v_pk_mul_f32 v[4:5], v[4:5], v[98:99] op_sel_hi:[1,0]
	v_cvt_pk_bf16_f32 v2, v2, v3
	v_cvt_pk_bf16_f32 v3, v4, v5
	v_pk_mul_f32 v[6:7], v[6:7], v[98:99] op_sel_hi:[1,0]
	v_pk_mul_f32 v[8:9], v[8:9], v[98:99] op_sel_hi:[1,0]
	v_cvt_pk_bf16_f32 v4, v6, v7
	v_cvt_pk_bf16_f32 v5, v8, v9
	s_nop 1
	v_permlane32_swap_b32 v2, v4
	v_permlane32_swap_b32 v3, v5
	global_store_dwordx4 v[100:101], v[2:5], off
	v_pk_mul_f32 v[10:11], v[10:11], v[98:99] op_sel_hi:[1,0]
	v_pk_mul_f32 v[12:13], v[12:13], v[98:99] op_sel_hi:[1,0]
	v_cvt_pk_bf16_f32 v6, v10, v11
	v_cvt_pk_bf16_f32 v7, v12, v13
	v_pk_mul_f32 v[14:15], v[14:15], v[98:99] op_sel_hi:[1,0]
	v_pk_mul_f32 v[16:17], v[16:17], v[98:99] op_sel_hi:[1,0]
	v_cvt_pk_bf16_f32 v8, v14, v15
	v_cvt_pk_bf16_f32 v9, v16, v17
	s_nop 1
	v_permlane32_swap_b32 v6, v8
	v_permlane32_swap_b32 v7, v9
	global_store_dwordx4 v[100:101], v[6:9], off offset:32
	s_waitcnt lgkmcnt(0)
	s_barrier
	s_cbranch_scc1 .LBB0_653
